# bf16 GEMM epilogues: removed the in-place add of the null bias (literal 0.0), store-data hazard pads kept
# baseline (speedup 1.0000x reference)
.LBB0_46:
	v_lshl_add_u32 v144, s18, 8, v159
	v_lshl_or_b32 v140, s44, 8, v163
	v_ashrrev_i32_e32 v141, 31, v140
	v_ashrrev_i32_e32 v145, 31, v144
	v_lshl_add_u64 v[142:143], v[140:141], 1, s[6:7]
	v_lshlrev_b64 v[140:141], 13, v[144:145]
	v_max_f32_e32 v127, 0, v127
	v_max_f32_e32 v126, 0, v126
	v_max_f32_e32 v129, 0, v129
	v_max_f32_e32 v128, 0, v128
	v_max_f32_e32 v123, 0, v123
	v_max_f32_e32 v122, 0, v122
	v_max_f32_e32 v125, 0, v125
	v_max_f32_e32 v124, 0, v124
	v_lshl_add_u64 v[140:141], v[142:143], 0, v[140:141]
	v_pk_mul_f32 v[128:129], v[128:129], v[128:129]
	v_pk_mul_f32 v[126:127], v[126:127], v[126:127]
	v_pk_mul_f32 v[146:147], v[124:125], v[124:125]
	v_pk_mul_f32 v[124:125], v[122:123], v[122:123]
	v_cvt_pk_bf16_f32 v122, v126, v127
	v_cvt_pk_bf16_f32 v123, v128, v129
	v_max_f32_e32 v119, 0, v119
	v_max_f32_e32 v118, 0, v118
	v_max_f32_e32 v115, 0, v115
	v_max_f32_e32 v114, 0, v114
	v_max_f32_e32 v117, 0, v117
	v_max_f32_e32 v116, 0, v116
	v_cvt_pk_bf16_f32 v124, v124, v125
	v_cvt_pk_bf16_f32 v125, v146, v147
	global_store_dwordx4 v[140:141], v[122:125], off nt
	v_max_f32_e32 v121, 0, v121
	v_max_f32_e32 v120, 0, v120
	v_pk_mul_f32 v[118:119], v[118:119], v[118:119]
	v_pk_mul_f32 v[122:123], v[116:117], v[116:117]
	v_pk_mul_f32 v[116:117], v[114:115], v[114:115]
	v_cvt_pk_bf16_f32 v114, v118, v119
	v_pk_mul_f32 v[120:121], v[120:121], v[120:121]
	v_cvt_pk_bf16_f32 v115, v120, v121
	v_cvt_pk_bf16_f32 v116, v116, v117
	v_cvt_pk_bf16_f32 v117, v122, v123
	global_store_dwordx4 v[140:141], v[114:117], off offset:256 nt
	s_nop 1
	v_or_b32_e32 v114, 16, v144
	v_ashrrev_i32_e32 v115, 31, v114
	v_lshlrev_b64 v[114:115], 13, v[114:115]
	v_max_f32_e32 v111, 0, v111
	v_max_f32_e32 v110, 0, v110
	v_max_f32_e32 v113, 0, v113
	v_max_f32_e32 v112, 0, v112
	v_max_f32_e32 v107, 0, v107
	v_max_f32_e32 v106, 0, v106
	v_max_f32_e32 v109, 0, v109
	v_max_f32_e32 v108, 0, v108
	v_lshl_add_u64 v[114:115], v[142:143], 0, v[114:115]
	v_pk_mul_f32 v[112:113], v[112:113], v[112:113]
	v_pk_mul_f32 v[110:111], v[110:111], v[110:111]
	v_pk_mul_f32 v[116:117], v[108:109], v[108:109]
	v_pk_mul_f32 v[108:109], v[106:107], v[106:107]
	v_cvt_pk_bf16_f32 v106, v110, v111
	v_cvt_pk_bf16_f32 v107, v112, v113
	v_max_f32_e32 v103, 0, v103
	v_max_f32_e32 v102, 0, v102
	v_max_f32_e32 v99, 0, v99
	v_max_f32_e32 v98, 0, v98
	v_max_f32_e32 v101, 0, v101
	v_max_f32_e32 v100, 0, v100
	v_cvt_pk_bf16_f32 v108, v108, v109
	v_cvt_pk_bf16_f32 v109, v116, v117
	global_store_dwordx4 v[114:115], v[106:109], off nt
	v_max_f32_e32 v105, 0, v105
	v_max_f32_e32 v104, 0, v104
	v_pk_mul_f32 v[102:103], v[102:103], v[102:103]
	v_pk_mul_f32 v[106:107], v[100:101], v[100:101]
	v_pk_mul_f32 v[100:101], v[98:99], v[98:99]
	v_cvt_pk_bf16_f32 v98, v102, v103
	v_pk_mul_f32 v[104:105], v[104:105], v[104:105]
	v_cvt_pk_bf16_f32 v99, v104, v105
	v_cvt_pk_bf16_f32 v100, v100, v101
	v_cvt_pk_bf16_f32 v101, v106, v107
	global_store_dwordx4 v[114:115], v[98:101], off offset:256 nt
	s_nop 1
	v_or_b32_e32 v98, 32, v144
	v_ashrrev_i32_e32 v99, 31, v98
	v_lshlrev_b64 v[98:99], 13, v[98:99]
	v_max_f32_e32 v95, 0, v95
	v_max_f32_e32 v94, 0, v94
	v_max_f32_e32 v97, 0, v97
	v_max_f32_e32 v96, 0, v96
	v_max_f32_e32 v91, 0, v91
	v_max_f32_e32 v90, 0, v90
	v_max_f32_e32 v93, 0, v93
	v_max_f32_e32 v92, 0, v92
	v_lshl_add_u64 v[98:99], v[142:143], 0, v[98:99]
	v_pk_mul_f32 v[96:97], v[96:97], v[96:97]
	v_pk_mul_f32 v[94:95], v[94:95], v[94:95]
	v_pk_mul_f32 v[100:101], v[92:93], v[92:93]
	v_pk_mul_f32 v[92:93], v[90:91], v[90:91]
	v_cvt_pk_bf16_f32 v90, v94, v95
	v_cvt_pk_bf16_f32 v91, v96, v97
	v_max_f32_e32 v87, 0, v87
	v_max_f32_e32 v86, 0, v86
	v_max_f32_e32 v83, 0, v83
	v_max_f32_e32 v82, 0, v82
	v_max_f32_e32 v85, 0, v85
	v_max_f32_e32 v84, 0, v84
	v_cvt_pk_bf16_f32 v92, v92, v93
	v_cvt_pk_bf16_f32 v93, v100, v101
	global_store_dwordx4 v[98:99], v[90:93], off nt
	v_max_f32_e32 v89, 0, v89
	v_max_f32_e32 v88, 0, v88
	v_pk_mul_f32 v[86:87], v[86:87], v[86:87]
	v_pk_mul_f32 v[90:91], v[84:85], v[84:85]
	v_pk_mul_f32 v[84:85], v[82:83], v[82:83]
	v_cvt_pk_bf16_f32 v82, v86, v87
	v_pk_mul_f32 v[88:89], v[88:89], v[88:89]
	v_cvt_pk_bf16_f32 v83, v88, v89
	v_cvt_pk_bf16_f32 v84, v84, v85
	v_cvt_pk_bf16_f32 v85, v90, v91
	global_store_dwordx4 v[98:99], v[82:85], off offset:256 nt
	s_nop 1
	v_or_b32_e32 v82, 48, v144
	v_ashrrev_i32_e32 v83, 31, v82
	v_lshlrev_b64 v[82:83], 13, v[82:83]
	v_max_f32_e32 v79, 0, v79
	v_max_f32_e32 v78, 0, v78
	v_max_f32_e32 v81, 0, v81
	v_max_f32_e32 v80, 0, v80
	v_max_f32_e32 v75, 0, v75
	v_max_f32_e32 v74, 0, v74
	v_max_f32_e32 v77, 0, v77
	v_max_f32_e32 v76, 0, v76
	v_lshl_add_u64 v[82:83], v[142:143], 0, v[82:83]
	v_pk_mul_f32 v[80:81], v[80:81], v[80:81]
	v_pk_mul_f32 v[78:79], v[78:79], v[78:79]
	v_pk_mul_f32 v[84:85], v[76:77], v[76:77]
	v_pk_mul_f32 v[76:77], v[74:75], v[74:75]
	v_cvt_pk_bf16_f32 v74, v78, v79
	v_cvt_pk_bf16_f32 v75, v80, v81
	v_max_f32_e32 v67, 0, v67
	v_max_f32_e32 v66, 0, v66
	v_max_f32_e32 v69, 0, v69
	v_max_f32_e32 v68, 0, v68
	v_cvt_pk_bf16_f32 v76, v76, v77
	v_cvt_pk_bf16_f32 v77, v84, v85
	global_store_dwordx4 v[82:83], v[74:77], off nt
	v_max_f32_e32 v71, 0, v71
	v_max_f32_e32 v70, 0, v70
	v_max_f32_e32 v73, 0, v73
	v_max_f32_e32 v72, 0, v72
	v_pk_mul_f32 v[74:75], v[68:69], v[68:69]
	v_pk_mul_f32 v[68:69], v[66:67], v[66:67]
	v_max_f32_e32 v63, 0, v63
	v_max_f32_e32 v62, 0, v62
	v_pk_mul_f32 v[72:73], v[72:73], v[72:73]
	v_pk_mul_f32 v[70:71], v[70:71], v[70:71]
	v_cvt_pk_bf16_f32 v66, v70, v71
	v_cvt_pk_bf16_f32 v67, v72, v73
	v_cvt_pk_bf16_f32 v68, v68, v69
	v_cvt_pk_bf16_f32 v69, v74, v75
	v_max_f32_e32 v59, 0, v59
	v_max_f32_e32 v58, 0, v58
	v_max_f32_e32 v61, 0, v61
	v_max_f32_e32 v60, 0, v60
	v_pk_mul_f32 v[62:63], v[62:63], v[62:63]
	s_mov_b32 s11, 0x100000
	global_store_dwordx4 v[82:83], v[66:69], off offset:256 nt
	v_max_f32_e32 v65, 0, v65
	v_max_f32_e32 v64, 0, v64
	v_pk_mul_f32 v[68:69], v[60:61], v[60:61]
	v_pk_mul_f32 v[60:61], v[58:59], v[58:59]
	v_cvt_pk_bf16_f32 v58, v62, v63
	v_add_co_u32_e32 v62, vcc, s11, v140
	v_pk_mul_f32 v[64:65], v[64:65], v[64:65]
	v_addc_co_u32_e32 v63, vcc, 0, v141, vcc
	v_cvt_pk_bf16_f32 v59, v64, v65
	v_max_f32_e32 v51, 0, v51
	v_max_f32_e32 v50, 0, v50
	v_max_f32_e32 v53, 0, v53
	v_max_f32_e32 v52, 0, v52
	s_mov_b64 s[20:21], 0x100000
	v_cvt_pk_bf16_f32 v60, v60, v61
	v_cvt_pk_bf16_f32 v61, v68, v69
	global_store_dwordx4 v[62:63], v[58:61], off nt
	v_max_f32_e32 v55, 0, v55
	v_max_f32_e32 v54, 0, v54
	v_max_f32_e32 v57, 0, v57
	v_max_f32_e32 v56, 0, v56
	v_pk_mul_f32 v[58:59], v[52:53], v[52:53]
	v_pk_mul_f32 v[52:53], v[50:51], v[50:51]
	v_max_f32_e32 v47, 0, v47
	v_max_f32_e32 v46, 0, v46
	v_lshl_add_u64 v[66:67], v[140:141], 0, s[20:21]
	v_pk_mul_f32 v[56:57], v[56:57], v[56:57]
	v_pk_mul_f32 v[54:55], v[54:55], v[54:55]
	v_cvt_pk_bf16_f32 v50, v54, v55
	v_cvt_pk_bf16_f32 v51, v56, v57
	v_cvt_pk_bf16_f32 v52, v52, v53
	v_cvt_pk_bf16_f32 v53, v58, v59
	v_max_f32_e32 v43, 0, v43
	v_max_f32_e32 v42, 0, v42
	v_max_f32_e32 v45, 0, v45
	v_max_f32_e32 v44, 0, v44
	v_pk_mul_f32 v[46:47], v[46:47], v[46:47]
	s_mov_b32 s11, 0x120000
	global_store_dwordx4 v[66:67], v[50:53], off offset:256 nt
	v_max_f32_e32 v49, 0, v49
	v_max_f32_e32 v48, 0, v48
	v_pk_mul_f32 v[52:53], v[44:45], v[44:45]
	v_pk_mul_f32 v[44:45], v[42:43], v[42:43]
	v_cvt_pk_bf16_f32 v42, v46, v47
	v_add_co_u32_e32 v46, vcc, s11, v140
	v_pk_mul_f32 v[48:49], v[48:49], v[48:49]
	v_addc_co_u32_e32 v47, vcc, 0, v141, vcc
	v_cvt_pk_bf16_f32 v43, v48, v49
	v_max_f32_e32 v35, 0, v35
	v_max_f32_e32 v34, 0, v34
	v_max_f32_e32 v37, 0, v37
	v_max_f32_e32 v36, 0, v36
	s_mov_b64 s[20:21], 0x120000
	v_cvt_pk_bf16_f32 v44, v44, v45
	v_cvt_pk_bf16_f32 v45, v52, v53
	global_store_dwordx4 v[46:47], v[42:45], off nt
	v_max_f32_e32 v39, 0, v39
	v_max_f32_e32 v38, 0, v38
	v_max_f32_e32 v41, 0, v41
	v_max_f32_e32 v40, 0, v40
	v_pk_mul_f32 v[42:43], v[36:37], v[36:37]
	v_pk_mul_f32 v[36:37], v[34:35], v[34:35]
	v_max_f32_e32 v31, 0, v31
	v_max_f32_e32 v30, 0, v30
	v_lshl_add_u64 v[50:51], v[140:141], 0, s[20:21]
	v_pk_mul_f32 v[40:41], v[40:41], v[40:41]
	v_pk_mul_f32 v[38:39], v[38:39], v[38:39]
	v_cvt_pk_bf16_f32 v34, v38, v39
	v_cvt_pk_bf16_f32 v35, v40, v41
	v_cvt_pk_bf16_f32 v36, v36, v37
	v_cvt_pk_bf16_f32 v37, v42, v43
	v_max_f32_e32 v27, 0, v27
	v_max_f32_e32 v26, 0, v26
	v_max_f32_e32 v29, 0, v29
	v_max_f32_e32 v28, 0, v28
	v_pk_mul_f32 v[30:31], v[30:31], v[30:31]
	s_mov_b32 s11, 0x140000
	global_store_dwordx4 v[50:51], v[34:37], off offset:256 nt
	v_max_f32_e32 v33, 0, v33
	v_max_f32_e32 v32, 0, v32
	v_pk_mul_f32 v[36:37], v[28:29], v[28:29]
	v_pk_mul_f32 v[28:29], v[26:27], v[26:27]
	v_cvt_pk_bf16_f32 v26, v30, v31
	v_add_co_u32_e32 v30, vcc, s11, v140
	v_pk_mul_f32 v[32:33], v[32:33], v[32:33]
	v_addc_co_u32_e32 v31, vcc, 0, v141, vcc
	v_cvt_pk_bf16_f32 v27, v32, v33
	v_max_f32_e32 v19, 0, v19
	v_max_f32_e32 v18, 0, v18
	v_max_f32_e32 v21, 0, v21
	v_max_f32_e32 v20, 0, v20
	s_mov_b64 s[20:21], 0x140000
	v_cvt_pk_bf16_f32 v28, v28, v29
	v_cvt_pk_bf16_f32 v29, v36, v37
	global_store_dwordx4 v[30:31], v[26:29], off nt
	v_max_f32_e32 v23, 0, v23
	v_max_f32_e32 v22, 0, v22
	v_max_f32_e32 v25, 0, v25
	v_max_f32_e32 v24, 0, v24
	v_pk_mul_f32 v[26:27], v[20:21], v[20:21]
	v_pk_mul_f32 v[20:21], v[18:19], v[18:19]
	v_max_f32_e32 v15, 0, v15
	v_max_f32_e32 v14, 0, v14
	v_lshl_add_u64 v[34:35], v[140:141], 0, s[20:21]
	v_pk_mul_f32 v[24:25], v[24:25], v[24:25]
	v_pk_mul_f32 v[22:23], v[22:23], v[22:23]
	v_cvt_pk_bf16_f32 v18, v22, v23
	v_cvt_pk_bf16_f32 v19, v24, v25
	v_cvt_pk_bf16_f32 v20, v20, v21
	v_cvt_pk_bf16_f32 v21, v26, v27
	v_max_f32_e32 v11, 0, v11
	v_max_f32_e32 v10, 0, v10
	v_max_f32_e32 v13, 0, v13
	v_max_f32_e32 v12, 0, v12
	v_pk_mul_f32 v[14:15], v[14:15], v[14:15]
	s_mov_b32 s11, 0x160000
	global_store_dwordx4 v[34:35], v[18:21], off offset:256 nt
	v_max_f32_e32 v17, 0, v17
	v_max_f32_e32 v16, 0, v16
	v_pk_mul_f32 v[20:21], v[12:13], v[12:13]
	v_pk_mul_f32 v[12:13], v[10:11], v[10:11]
	v_cvt_pk_bf16_f32 v10, v14, v15
	v_add_co_u32_e32 v14, vcc, s11, v140
	s_mov_b64 s[20:21], 0x160000
	v_pk_mul_f32 v[16:17], v[16:17], v[16:17]
	v_addc_co_u32_e32 v15, vcc, 0, v141, vcc
	v_cvt_pk_bf16_f32 v11, v16, v17
	v_max_f32_e32 v3, 0, v3
	v_max_f32_e32 v2, 0, v2
	v_max_f32_e32 v5, 0, v5
	v_max_f32_e32 v4, 0, v4
	v_lshl_add_u64 v[18:19], v[140:141], 0, s[20:21]
	v_cvt_pk_bf16_f32 v12, v12, v13
	v_cvt_pk_bf16_f32 v13, v20, v21
	global_store_dwordx4 v[14:15], v[10:13], off nt
	v_max_f32_e32 v7, 0, v7
	v_max_f32_e32 v6, 0, v6
	v_max_f32_e32 v9, 0, v9
	v_max_f32_e32 v8, 0, v8
	v_pk_mul_f32 v[10:11], v[4:5], v[4:5]
	v_pk_mul_f32 v[4:5], v[2:3], v[2:3]
	s_andn2_b64 vcc, exec, s[0:1]
	s_mov_b64 s[0:1], -1
	s_movk_i32 s55, 0xf000
	v_pk_mul_f32 v[8:9], v[8:9], v[8:9]
	v_pk_mul_f32 v[6:7], v[6:7], v[6:7]
	s_nop 0
	v_cvt_pk_bf16_f32 v2, v6, v7
	v_cvt_pk_bf16_f32 v3, v8, v9
	v_cvt_pk_bf16_f32 v4, v4, v5
	v_cvt_pk_bf16_f32 v5, v10, v11
	global_store_dwordx4 v[18:19], v[2:5], off offset:256 nt
	s_mov_b32 s98, 1
	s_cbranch_vccnz .LBB0_35
	s_andn2_b64 vcc, exec, s[4:5]
	s_cbranch_vccnz .LBB0_34
	s_barrier
	s_branch .LBB0_34

.LBB0_356:
	v_lshl_or_b32 v140, s44, 8, v144
	v_ashrrev_i32_e32 v141, 31, v140
	v_lshl_add_u32 v154, s18, 8, v142
	v_lshl_add_u64 v[140:141], v[140:141], 1, s[6:7]
	s_movk_i32 s11, 0x1800
	v_mad_i64_i32 v[146:147], s[20:21], v154, s11, v[140:141]
	v_pk_add_f32 v[148:149], v[124:125], 0 op_sel_hi:[1,0]
	v_pk_add_f32 v[124:125], v[122:123], 0 op_sel_hi:[1,0]
	v_cvt_pk_bf16_f32 v122, v126, v127
	v_cvt_pk_bf16_f32 v123, v128, v129
	v_cvt_pk_bf16_f32 v124, v124, v125
	v_cvt_pk_bf16_f32 v125, v148, v149
	global_store_dwordx4 v[146:147], v[122:125], off nt
	s_nop 1
	v_pk_add_f32 v[122:123], v[112:113], 0 op_sel_hi:[1,0]
	v_pk_add_f32 v[112:113], v[110:111], 0 op_sel_hi:[1,0]
	v_cvt_pk_bf16_f32 v110, v118, v119
	v_cvt_pk_bf16_f32 v111, v120, v121
	v_cvt_pk_bf16_f32 v112, v112, v113
	v_cvt_pk_bf16_f32 v113, v122, v123
	global_store_dwordx4 v[146:147], v[110:113], off offset:256 nt
	s_nop 1
	v_or_b32_e32 v110, 16, v154
	v_mad_i64_i32 v[110:111], s[20:21], v110, s11, v[140:141]
	v_pk_add_f32 v[112:113], v[116:117], 0 op_sel_hi:[1,0]
	v_pk_add_f32 v[116:117], v[108:109], 0 op_sel_hi:[1,0]
	v_pk_add_f32 v[108:109], v[106:107], 0 op_sel_hi:[1,0]
	v_cvt_pk_bf16_f32 v106, v114, v115
	v_cvt_pk_bf16_f32 v107, v112, v113
	v_cvt_pk_bf16_f32 v108, v108, v109
	v_cvt_pk_bf16_f32 v109, v116, v117
	global_store_dwordx4 v[110:111], v[106:109], off nt
	s_nop 1
	v_pk_add_f32 v[106:107], v[96:97], 0 op_sel_hi:[1,0]
	v_pk_add_f32 v[96:97], v[94:95], 0 op_sel_hi:[1,0]
	v_cvt_pk_bf16_f32 v94, v102, v103
	v_cvt_pk_bf16_f32 v95, v104, v105
	v_cvt_pk_bf16_f32 v96, v96, v97
	v_cvt_pk_bf16_f32 v97, v106, v107
	global_store_dwordx4 v[110:111], v[94:97], off offset:256 nt
	s_nop 1
	v_or_b32_e32 v94, 32, v154
	v_mad_i64_i32 v[94:95], s[20:21], v94, s11, v[140:141]
	v_pk_add_f32 v[96:97], v[100:101], 0 op_sel_hi:[1,0]
	v_pk_add_f32 v[100:101], v[92:93], 0 op_sel_hi:[1,0]
	v_pk_add_f32 v[92:93], v[90:91], 0 op_sel_hi:[1,0]
	v_cvt_pk_bf16_f32 v90, v98, v99
	v_cvt_pk_bf16_f32 v91, v96, v97
	v_cvt_pk_bf16_f32 v92, v92, v93
	v_cvt_pk_bf16_f32 v93, v100, v101
	global_store_dwordx4 v[94:95], v[90:93], off nt
	s_nop 1
	v_pk_add_f32 v[90:91], v[80:81], 0 op_sel_hi:[1,0]
	v_pk_add_f32 v[80:81], v[78:79], 0 op_sel_hi:[1,0]
	v_cvt_pk_bf16_f32 v78, v86, v87
	v_cvt_pk_bf16_f32 v79, v88, v89
	v_cvt_pk_bf16_f32 v80, v80, v81
	v_cvt_pk_bf16_f32 v81, v90, v91
	global_store_dwordx4 v[94:95], v[78:81], off offset:256 nt
	s_nop 1
	v_or_b32_e32 v78, 48, v154
	v_mad_i64_i32 v[78:79], s[20:21], v78, s11, v[140:141]
	v_pk_add_f32 v[80:81], v[84:85], 0 op_sel_hi:[1,0]
	v_pk_add_f32 v[84:85], v[76:77], 0 op_sel_hi:[1,0]
	v_pk_add_f32 v[76:77], v[74:75], 0 op_sel_hi:[1,0]
	v_cvt_pk_bf16_f32 v74, v82, v83
	v_cvt_pk_bf16_f32 v75, v80, v81
	v_cvt_pk_bf16_f32 v76, v76, v77
	v_cvt_pk_bf16_f32 v77, v84, v85
	global_store_dwordx4 v[78:79], v[74:77], off nt
	s_nop 1
	v_pk_add_f32 v[74:75], v[68:69], 0 op_sel_hi:[1,0]
	v_pk_add_f32 v[68:69], v[66:67], 0 op_sel_hi:[1,0]
	v_cvt_pk_bf16_f32 v66, v70, v71
	v_cvt_pk_bf16_f32 v67, v72, v73
	v_cvt_pk_bf16_f32 v68, v68, v69
	v_cvt_pk_bf16_f32 v69, v74, v75
	global_store_dwordx4 v[78:79], v[66:69], off offset:256 nt
	s_andn2_b64 vcc, exec, s[0:1]
	s_mov_b64 s[0:1], -1
	v_add_u32_e32 v66, 0x80, v154
	v_mad_i64_i32 v[66:67], s[20:21], v66, s11, v[140:141]
	v_pk_add_f32 v[68:69], v[60:61], 0 op_sel_hi:[1,0]
	v_pk_add_f32 v[60:61], v[58:59], 0 op_sel_hi:[1,0]
	v_cvt_pk_bf16_f32 v58, v62, v63
	v_cvt_pk_bf16_f32 v59, v64, v65
	s_movk_i32 s46, 0xd000
	v_cvt_pk_bf16_f32 v60, v60, v61
	v_cvt_pk_bf16_f32 v61, v68, v69
	global_store_dwordx4 v[66:67], v[58:61], off nt
	s_movk_i32 s47, 0xec00
	s_movk_i32 s55, 0xf000
	v_pk_add_f32 v[58:59], v[48:49], 0 op_sel_hi:[1,0]
	v_pk_add_f32 v[48:49], v[46:47], 0 op_sel_hi:[1,0]
	v_cvt_pk_bf16_f32 v46, v54, v55
	v_cvt_pk_bf16_f32 v47, v56, v57
	v_cvt_pk_bf16_f32 v48, v48, v49
	v_cvt_pk_bf16_f32 v49, v58, v59
	global_store_dwordx4 v[66:67], v[46:49], off offset:256 nt
	s_nop 1
	s_nop 0
	v_add_u32_e32 v46, 0x90, v154
	v_mad_i64_i32 v[46:47], s[20:21], v46, s11, v[140:141]
	v_pk_add_f32 v[48:49], v[52:53], 0 op_sel_hi:[1,0]
	v_pk_add_f32 v[52:53], v[44:45], 0 op_sel_hi:[1,0]
	v_pk_add_f32 v[44:45], v[42:43], 0 op_sel_hi:[1,0]
	v_cvt_pk_bf16_f32 v42, v50, v51
	v_cvt_pk_bf16_f32 v43, v48, v49
	s_nop 0
	v_cvt_pk_bf16_f32 v44, v44, v45
	v_cvt_pk_bf16_f32 v45, v52, v53
	global_store_dwordx4 v[46:47], v[42:45], off nt
	s_nop 1
	s_nop 1
	v_pk_add_f32 v[42:43], v[32:33], 0 op_sel_hi:[1,0]
	v_pk_add_f32 v[32:33], v[30:31], 0 op_sel_hi:[1,0]
	v_cvt_pk_bf16_f32 v30, v38, v39
	v_cvt_pk_bf16_f32 v31, v40, v41
	s_nop 0
	v_cvt_pk_bf16_f32 v32, v32, v33
	v_cvt_pk_bf16_f32 v33, v42, v43
	global_store_dwordx4 v[46:47], v[30:33], off offset:256 nt
	s_nop 1
	s_nop 1
	v_add_u32_e32 v30, 0xa0, v154
	v_mad_i64_i32 v[30:31], s[20:21], v30, s11, v[140:141]
	v_pk_add_f32 v[32:33], v[36:37], 0 op_sel_hi:[1,0]
	v_pk_add_f32 v[36:37], v[28:29], 0 op_sel_hi:[1,0]
	v_pk_add_f32 v[28:29], v[26:27], 0 op_sel_hi:[1,0]
	v_cvt_pk_bf16_f32 v26, v34, v35
	v_cvt_pk_bf16_f32 v27, v32, v33
	s_nop 0
	v_cvt_pk_bf16_f32 v28, v28, v29
	v_cvt_pk_bf16_f32 v29, v36, v37
	global_store_dwordx4 v[30:31], v[26:29], off nt
	s_nop 1
	s_nop 1
	v_pk_add_f32 v[26:27], v[16:17], 0 op_sel_hi:[1,0]
	v_pk_add_f32 v[16:17], v[14:15], 0 op_sel_hi:[1,0]
	v_cvt_pk_bf16_f32 v14, v22, v23
	v_cvt_pk_bf16_f32 v15, v24, v25
	s_nop 0
	v_cvt_pk_bf16_f32 v16, v16, v17
	v_cvt_pk_bf16_f32 v17, v26, v27
	global_store_dwordx4 v[30:31], v[14:17], off offset:256 nt
	s_nop 1
	s_nop 1
	v_add_u32_e32 v14, 0xb0, v154
	v_mad_i64_i32 v[14:15], s[20:21], v14, s11, v[140:141]
	v_pk_add_f32 v[16:17], v[20:21], 0 op_sel_hi:[1,0]
	v_pk_add_f32 v[20:21], v[12:13], 0 op_sel_hi:[1,0]
	v_pk_add_f32 v[12:13], v[10:11], 0 op_sel_hi:[1,0]
	v_cvt_pk_bf16_f32 v10, v18, v19
	v_cvt_pk_bf16_f32 v11, v16, v17
	s_nop 0
	v_cvt_pk_bf16_f32 v12, v12, v13
	v_cvt_pk_bf16_f32 v13, v20, v21
	global_store_dwordx4 v[14:15], v[10:13], off nt
	s_nop 1
	s_nop 1
	v_pk_add_f32 v[10:11], v[4:5], 0 op_sel_hi:[1,0]
	v_pk_add_f32 v[4:5], v[2:3], 0 op_sel_hi:[1,0]
	v_cvt_pk_bf16_f32 v2, v6, v7
	v_cvt_pk_bf16_f32 v3, v8, v9
	s_nop 0
	v_cvt_pk_bf16_f32 v4, v4, v5
	v_cvt_pk_bf16_f32 v5, v10, v11
	global_store_dwordx4 v[14:15], v[2:5], off offset:256 nt
	s_mov_b32 s98, 1
	s_cbranch_vccnz .LBB0_349
	s_andn2_b64 vcc, exec, s[4:5]
	s_cbranch_vccnz .LBB0_348
	s_barrier
	s_branch .LBB0_348
